# P3 barrier: the invalidate is issued at arrival (before polling / before the leader's write-back) so its latency hides behind the wait
# speedup vs baseline: 1.0032x; 1.0018x over previous
.LBB0_877:
	s_lshl_b32 s6, s6, 6
	s_add_i32 s82, s6, 0x500
	s_lshl_b64 s[8:9], s[82:83], 2
	s_add_u32 s8, s54, s8
	s_addc_u32 s9, s55, s9
	v_mov_b64_e32 v[4:5], s[8:9]
	flat_atomic_add v3, v[4:5], v228 sc0
	v_cvt_f32_u32_e32 v1, v2
	v_sub_u32_e32 v4, 0, v2
	v_rcp_iflag_f32_e32 v1, v1
	s_nop 0
	v_mul_f32_e32 v1, 0x4f7ffffe, v1
	v_cvt_u32_f32_e32 v1, v1
	v_mul_lo_u32 v4, v4, v1
	v_mul_hi_u32 v4, v1, v4
	v_add_u32_e32 v1, v1, v4
	s_waitcnt vmcnt(0) lgkmcnt(0)
	v_mul_hi_u32 v1, v3, v1
	v_mul_lo_u32 v4, v1, v2
	v_sub_u32_e32 v4, v3, v4
	v_cmp_ge_u32_e32 vcc, v4, v2
	v_add_u32_e32 v5, 1, v1
	s_nop 0
	v_cndmask_b32_e32 v1, v1, v5, vcc
	v_sub_u32_e32 v5, v4, v2
	v_cndmask_b32_e32 v4, v4, v5, vcc
	v_cmp_ge_u32_e32 vcc, v4, v2
	v_add_u32_e32 v4, 1, v1
	s_nop 0
	v_cndmask_b32_e32 v1, v1, v4, vcc
	v_add_u32_e32 v4, 1, v3
	v_mad_u64_u32 v[2:3], s[8:9], v2, v1, v[2:3]
	v_cmp_ne_u32_e32 vcc, v4, v2
	s_and_saveexec_b64 s[8:9], vcc
	s_xor_b64 s[12:13], exec, s[8:9]
	s_cbranch_execz .LBB0_890
	s_add_i32 s82, s6, 0x900
	s_lshl_b64 s[8:9], s[82:83], 2
	s_add_u32 s16, s54, 0x3400
	s_addc_u32 s17, s55, 0
	v_mov_b32_e32 v4, s101
	v_mad_u32_u24 v4, v4, v0, v0
	s_add_i32 s101, s101, 1
	v_mov_b64_e32 v[2:3], s[16:17]
	buffer_inv sc1
	flat_load_dword v0, v[2:3] sc1
	s_waitcnt vmcnt(0) lgkmcnt(0)
	v_cmp_lt_u32_e32 vcc, v0, v4
	s_and_saveexec_b64 s[14:15], vcc
	s_cbranch_execz .LBB0_889
	s_mov_b32 s7, 1
	s_mov_b64 s[18:19], 0
	s_branch .LBB0_881

.LBB0_890:
	s_andn2_saveexec_b64 s[8:9], s[12:13]
	s_cbranch_execz .LBB0_906
	s_add_i32 s101, s101, 1
	v_mov_b32_e32 v1, s54
	v_add_co_u32_e32 v2, vcc, 0x3000, v1
	v_mov_b32_e32 v1, s55
	buffer_inv sc1
	buffer_wbl2 sc1
	s_waitcnt vmcnt(0)
	v_addc_co_u32_e32 v3, vcc, 0, v1, vcc
	flat_atomic_add v1, v[2:3], v228 offset:1024 sc0
	v_cvt_f32_u32_e32 v2, v0
	v_sub_u32_e32 v3, 0, v0
	s_add_u32 s12, s54, 0x3400
	s_addc_u32 s13, s55, 0
	v_rcp_iflag_f32_e32 v2, v2
	s_mov_b64 s[16:17], -1
	v_mul_f32_e32 v2, 0x4f7ffffe, v2
	v_cvt_u32_f32_e32 v2, v2
	v_mul_lo_u32 v3, v3, v2
	v_mul_hi_u32 v3, v2, v3
	v_add_u32_e32 v2, v2, v3
	s_waitcnt vmcnt(0) lgkmcnt(0)
	v_mul_hi_u32 v2, v1, v2
	v_mul_lo_u32 v3, v2, v0
	v_sub_u32_e32 v3, v1, v3
	v_cmp_ge_u32_e32 vcc, v3, v0
	v_add_u32_e32 v4, 1, v2
	s_nop 0
	v_cndmask_b32_e32 v2, v2, v4, vcc
	v_sub_u32_e32 v4, v3, v0
	v_cndmask_b32_e32 v3, v3, v4, vcc
	v_cmp_ge_u32_e32 vcc, v3, v0
	v_add_u32_e32 v3, 1, v2
	s_nop 0
	v_cndmask_b32_e32 v2, v2, v3, vcc
	v_add_u32_e32 v3, 1, v1
	v_mad_u64_u32 v[0:1], s[8:9], v0, v2, v[0:1]
	v_cmp_ne_u32_e32 vcc, v3, v0
	v_mov_b32_e32 v3, v0
	v_mov_b64_e32 v[0:1], s[12:13]
	s_and_saveexec_b64 s[14:15], vcc
	s_cbranch_execz .LBB0_903
	v_mov_b64_e32 v[0:1], s[12:13]
	flat_load_dword v0, v[0:1] sc1
	s_mov_b64 s[20:21], 0
	s_waitcnt vmcnt(0) lgkmcnt(0)
	v_cmp_lt_u32_e32 vcc, v0, v3
	s_and_saveexec_b64 s[18:19], vcc
	s_cbranch_execz .LBB0_902
	s_add_u32 s16, s54, 0x200
	s_addc_u32 s17, s55, 0
	s_mov_b32 s7, 1
	s_branch .LBB0_895
